# EpiResid epilogue: all residual loads issued up front with counted vmcnt waits (bf16 path 16 loads, f32 path software-pipelined); GDN chunk-loop vmcnt(0) hoisted to preheader
# speedup vs baseline: 1.0095x; 1.0095x over previous
; DI void gdn_unit(const Params& P, bf16_t* proj, const float* gb, int b, int h, LAS unsigned char* lds) {
;     ...
;     f32x4 Sacc[8];
; #pragma unroll
;     for (int i = 0; i < 8; ++i) Sacc[i] = (f32x4){0.f, 0.f, 0.f, 0.f};
;     const float Aneg = -__expf(P.in[25][h]), dtb = P.in[26][h];
;     const float ng = P.in[27][16 * wave + (lane0 & 15)];
;     const float* cwp = P.in[24] + h * 128 + 2 * lane0;
;     __syncthreads();
;     f32x2 cwr[3][4];
; #pragma unroll
;     for (int w = 0; w < 3; ++w)
; #pragma unroll
;         for (int j = 0; j < 4; ++j) cwr[w][j] = *(const f32x2*)(cwp + j * 3072 + w * 1024);
;     unsigned rawq[3][11]; float gbl, gai;
;     {
;         const int t00 = b * SEQ_;
; #pragma unroll
;         for (int w = 0; w < 3; ++w) {
;             const bf16_t* rbase = proj + (size_t)(t00 + wave * 8 - 3) * PJ1 + w * 1024 + h * 128;
; #pragma unroll
;             for (int i = 0; i < 11; ++i) rawq[w][i] = (wave * 8 - 3 + i >= 0) ? *(const unsigned*)(rbase + i * PJ1 + 2 * lane0) : 0u;
;         }
;         gbl = gb[(size_t)(t00 + lane0) * 16 + h]; gai = gb[(size_t)(t00 + lane0) * 16 + 8 + h];
;     }
.LBB0_413:
	v_or_b32_e32 v2, s8, v143
	v_ashrrev_i32_e32 v3, 31, v2
	v_readlane_b32 s6, v253, 10
	v_lshlrev_b64 v[2:3], 6, v[2:3]
	v_readlane_b32 s7, v253, 11
	s_and_b32 s0, s19, 0xfffff800
	s_ashr_i32 s1, s0, 31
	v_lshl_add_u64 v[2:3], s[6:7], 0, v[2:3]
	v_lshl_add_u64 v[2:3], v[2:3], 0, s[92:93]
	global_load_dword v203, v[2:3], off
	global_load_dword v204, v[2:3], off offset:32
	s_and_b32 s3, s73, 7
	s_or_b32 s42, s0, 64
	s_lshl_b64 s[0:1], s[0:1], 13
	s_lshl_b32 s3, s3, 8
	s_lshl_b32 s2, s2, 1
	v_readlane_b32 s8, v253, 4
	v_readlane_b32 s9, v253, 5
	s_add_u32 s43, s8, s2
	s_addc_u32 s44, s9, 0
	s_add_u32 s6, s6, s92
	s_addc_u32 s7, s7, 0
	s_cmp_lt_u32 s14, 64
	s_cselect_b64 s[8:9], -1, 0
	s_cmp_gt_u32 s14, 63
	s_cselect_b64 s[10:11], -1, 0
	s_cmp_gt_i32 s15, 3
	s_cselect_b64 s[12:13], -1, 0
	s_cmp_lt_i32 s15, 4
	s_cselect_b32 s2, 0x4400, 0
	s_and_b32 s46, s4, 48
	s_add_i32 s45, s2, 0
	s_lshl_b32 s2, s46, 2
	s_add_i32 s48, s2, 0
	s_and_b32 s2, s14, 0x3fffffc0
	s_lshl_b32 s2, s2, 2
	s_ashr_i32 s5, s4, 31
	s_add_i32 s49, s2, 0
	v_mul_f32_e32 v1, 0x3fb8aa3b, v1
	s_add_i32 s47, s48, 0x24c00
	s_add_i32 s48, s48, 0x24d00
	s_add_i32 s49, s49, 0x25000
	s_or_b32 s0, s0, s3
	s_lshl_b64 s[2:3], s[4:5], 1
	v_exp_f32_e32 v192, v1
	s_add_u32 s0, s0, s2
	s_addc_u32 s1, s1, s3
	s_add_u32 s5, s88, s0
	s_mul_i32 s92, s15, 0x880
	s_waitcnt vmcnt(8)
	v_mov_b32_e32 v92, v79
	v_mov_b32_e32 v93, v79
	s_waitcnt vmcnt(7)
	v_mov_b32_e32 v94, v81
	v_mov_b32_e32 v95, v81
	s_waitcnt vmcnt(6)
	v_mov_b32_e32 v96, v83
	v_mov_b32_e32 v97, v83
	v_mov_b32_e32 v79, v78
	v_mov_b32_e32 v81, v80
	v_mov_b32_e32 v83, v82
	v_mov_b32_e32 v98, v76
	v_mov_b32_e32 v99, v76
	v_mov_b32_e32 v76, v77
	s_waitcnt vmcnt(5)
	v_mov_b32_e32 v100, v85
	v_mov_b32_e32 v101, v85
	s_waitcnt vmcnt(4)
	v_mov_b32_e32 v102, v87
	v_mov_b32_e32 v103, v87
	s_waitcnt vmcnt(3)
	v_mov_b32_e32 v104, v89
	v_mov_b32_e32 v105, v89
	s_waitcnt vmcnt(2)
	v_mov_b32_e32 v106, v91
	v_mov_b32_e32 v107, v91
	v_mov_b32_e32 v85, v84
	v_mov_b32_e32 v87, v86
	v_mov_b32_e32 v89, v88
	v_mov_b32_e32 v91, v90
	s_addc_u32 s69, s89, s1
	s_mov_b64 s[14:15], 0
	v_mov_b32_e32 v1, v0
	v_mov_b32_e32 v2, v0
	v_mov_b32_e32 v3, v0
	v_mov_b32_e32 v4, v0
	v_mov_b32_e32 v5, v0
	v_mov_b32_e32 v6, v0
	v_mov_b32_e32 v7, v0
	v_mov_b32_e32 v8, v0
	v_mov_b32_e32 v9, v0
	v_mov_b32_e32 v10, v0
	v_mov_b32_e32 v11, v0
	v_mov_b32_e32 v12, v0
	v_mov_b32_e32 v13, v0
	v_mov_b32_e32 v14, v0
	v_mov_b32_e32 v15, v0
	v_mov_b32_e32 v16, v0
	v_mov_b32_e32 v17, v0
	v_mov_b32_e32 v18, v0
	v_mov_b32_e32 v19, v0
	v_mov_b32_e32 v24, v0
	v_mov_b32_e32 v25, v0
	v_mov_b32_e32 v26, v0
	v_mov_b32_e32 v27, v0
	v_mov_b32_e32 v28, v0
	v_mov_b32_e32 v29, v0
	v_mov_b32_e32 v30, v0
	v_mov_b32_e32 v31, v0
	v_mov_b32_e32 v20, v0
	v_mov_b32_e32 v21, v0
	v_mov_b32_e32 v22, v0
	v_mov_b32_e32 v23, v0
	s_waitcnt vmcnt(0)
	s_branch .LBB0_415

; DI float sigmoidf_(float x) { return __builtin_amdgcn_rcpf(1.0f + __expf(-x)); }
; DI float log1p_fast(float e) { return e < 0.03125f ? e * (1.0f - e * (0.5f - e * (0.33333334f - 0.25f * e))) : __logf(1.0f + e); }
; DI float softplusf_(float x) { return x > 20.0f ? x : log1p_fast(__expf(x)); }
; DI void gdn_unit(const Params& P, bf16_t* proj, const float* gb, int b, int h, LAS unsigned char* lds) {
;     ...
;             const float bl = gbl, ai = gai;
;             beta = sigmoidf_(bl);
;             gc = Aneg * softplusf_(ai + dtb);
; #pragma unroll
.LBB0_415:
	v_add_f32_e32 v32, v154, v204
	s_mov_b32 s0, 0x41a00000
	v_mov_b32_e32 v67, v143
	v_cmp_nlt_f32_e32 vcc, s0, v32
	s_and_saveexec_b64 s[2:3], vcc
	s_cbranch_execz .LBB0_421
	v_mul_f32_e32 v32, 0x3fb8aa3b, v32
	v_exp_f32_e32 v33, v32
	s_mov_b32 s0, 0x3d000000
	v_cmp_ngt_f32_e32 vcc, s0, v33
	s_and_saveexec_b64 s[0:1], vcc
	s_xor_b64 s[16:17], exec, s[0:1]
	s_cbranch_execz .LBB0_418
	v_add_f32_e32 v32, 1.0, v33
	v_cmp_gt_f32_e32 vcc, s18, v32
	s_mov_b32 s0, 0x3f317217
	s_nop 0
	v_cndmask_b32_e64 v33, 0, 32, vcc
	v_ldexp_f32 v32, v32, v33
	v_log_f32_e32 v32, v32
	s_nop 0
	v_mul_f32_e32 v33, 0x3f317217, v32
	v_fma_f32 v33, v32, s0, -v33
	v_fmac_f32_e32 v33, 0x3377d1cf, v32
	s_mov_b32 s0, 0x7f800000
	v_fmac_f32_e32 v33, 0x3f317217, v32
	v_cmp_lt_f32_e64 s[0:1], |v32|, s0
	s_nop 1
	v_cndmask_b32_e64 v32, v32, v33, s[0:1]
	v_cndmask_b32_e32 v33, 0, v249, vcc
	v_sub_f32_e32 v32, v32, v33

; DI float bflo(unsigned w) { return __uint_as_float(w << 16); }
; DI float bfhi(unsigned w) { return __uint_as_float(w & 0xffff0000u); }
; DI unsigned cvt_pk_bf16(float lo, float hi) { unsigned r; asm volatile("v_cvt_pk_bf16_f32 %0, %1, %2" : "=v"(r) : "v"(lo), "v"(hi)); return r; }
;     DI void operator()(const f32x4 (&acc)[2][2][4][2], const pg8::Unit& u, int wr, int wc, int fr, int fq) const {
;         const int row0 = u.pm * 256 + wr * 64 + fr, col0 = u.pn * 256 + wc * 32 + 8 * fq;
;         const float sc = half ? 0.5f : 1.0f;
; #pragma unroll
;         for (int ai = 0; ai < 2; ++ai)
; #pragma unroll
;             for (int m = 0; m < 4; ++m) {
;                 const size_t off = (size_t)(row0 + ai * 128 + m * 16) * D_ + col0;
; #pragma unroll
;                 for (int bj = 0; bj < 2; ++bj) {
;                     const size_t o = off + bj * 128;
;                     f32x4 v0 = acc[ai][bj][m][0] * sc, v1 = acc[ai][bj][m][1] * sc;
;                     if (HAS_RES) {
;                         f32x4 r0, r1;
;                         if (resb) { const u32x4 rb = *(const u32x4*)(resb + o); r0 = (f32x4){bflo(rb.x), bfhi(rb.x), bflo(rb.y), bfhi(rb.y)}; r1 = (f32x4){bflo(rb.z), bfhi(rb.z), bflo(rb.w), bfhi(rb.w)}; }
;                         else { r0 = *(const f32x4*)(res + o); r1 = *(const f32x4*)(res + o + 4); }
;                         v0 = v0 + r0 * DN_ALPHA; v1 = v1 + r1 * DN_ALPHA;
;                     }
;                     u32x4 w; w.x = cvt_pk_bf16(v0[0], v0[1]); w.y = cvt_pk_bf16(v0[2], v0[3]); w.z = cvt_pk_bf16(v1[0], v1[1]); w.w = cvt_pk_bf16(v1[2], v1[3]);
;                     *(u32x4*)(out + o) = w;
;                 }
.LBB0_691:
	v_mov_b32_e32 v128, v163
	s_lshl_b32 s4, s72, 8
	s_add_i32 s4, s4, s77
	v_and_or_b32 v152, v128, 15, s4
	v_lshrrev_b32_e32 v128, 1, v128
	v_and_b32_e32 v128, 0x78, v128
	v_lshl_or_b32 v154, s70, 8, v128
	v_ashrrev_i32_e32 v153, 31, v152
	v_ashrrev_i32_e32 v155, 31, v154
	v_lshlrev_b64 v[128:129], 10, v[152:153]
	v_lshl_add_u64 v[160:161], v[128:129], 0, v[154:155]
	v_cndmask_b32_e64 v128, 0, 1, s[42:43]
	v_cmp_ne_u32_e64 s[4:5], 1, v128
	s_andn2_b64 vcc, exec, s[42:43]
	v_mov_b32_e32 v149, v148
	v_readlane_b32 s94, v255, 40
	v_readlane_b32 s95, v255, 41
	v_lshlrev_b32_e32 v245, 1, v160
	s_cbranch_vccnz .Lepr_f32
	v_mov_b32_e32 v244, v245
	global_load_dwordx4 v[180:183], v244, s[10:11]
	global_load_dwordx4 v[184:187], v244, s[10:11] offset:256
	v_add_u32_e32 v246, 0x8000, v245
	global_load_dwordx4 v[188:191], v246, s[10:11]
	global_load_dwordx4 v[192:195], v246, s[10:11] offset:256
	v_add_u32_e32 v244, 0x10000, v245
	global_load_dwordx4 v[196:199], v244, s[10:11]
	global_load_dwordx4 v[200:203], v244, s[10:11] offset:256
	v_add_u32_e32 v246, 0x18000, v245
	global_load_dwordx4 v[204:207], v246, s[10:11]
	global_load_dwordx4 v[208:211], v246, s[10:11] offset:256
	v_add_u32_e32 v244, 0x40000, v245
	global_load_dwordx4 v[212:215], v244, s[10:11]
	global_load_dwordx4 v[216:219], v244, s[10:11] offset:256
	v_add_u32_e32 v246, 0x48000, v245
	global_load_dwordx4 v[220:223], v246, s[10:11]
	global_load_dwordx4 v[224:227], v246, s[10:11] offset:256
	v_add_u32_e32 v244, 0x50000, v245
	global_load_dwordx4 v[228:231], v244, s[10:11]
	global_load_dwordx4 v[232:235], v244, s[10:11] offset:256
	v_add_u32_e32 v246, 0x58000, v245
	global_load_dwordx4 v[236:239], v246, s[10:11]
	global_load_dwordx4 v[240:243], v246, s[10:11] offset:256
	s_waitcnt vmcnt(15)
	v_lshlrev_b32_e32 v132, 16, v180
	v_and_b32_e32 v133, 0xffff0000, v180
	v_lshlrev_b32_e32 v134, 16, v181
	v_and_b32_e32 v135, 0xffff0000, v181
	v_lshlrev_b32_e32 v128, 16, v182
	v_and_b32_e32 v129, 0xffff0000, v182
	v_lshlrev_b32_e32 v130, 16, v183
	v_and_b32_e32 v131, 0xffff0000, v183
	v_mov_b32_e32 v244, v245
	v_pk_mul_f32 v[130:131], v[130:131], s[20:21] op_sel_hi:[1,0]
	v_pk_mul_f32 v[128:129], v[128:129], s[20:21] op_sel_hi:[1,0]
	v_pk_mul_f32 v[134:135], v[134:135], s[20:21] op_sel_hi:[1,0]
	v_pk_mul_f32 v[132:133], v[132:133], s[20:21] op_sel_hi:[1,0]
	v_pk_fma_f32 v[130:131], v[148:149], v[122:123], v[130:131]
	v_pk_fma_f32 v[122:123], v[150:151], v[120:121], v[128:129]
	v_pk_fma_f32 v[126:127], v[148:149], v[126:127], v[134:135]
	v_pk_fma_f32 v[124:125], v[150:151], v[124:125], v[132:133]
	v_cvt_pk_bf16_f32 v120, v124, v125
	v_cvt_pk_bf16_f32 v121, v126, v127
	v_cvt_pk_bf16_f32 v122, v122, v123
	v_cvt_pk_bf16_f32 v123, v130, v131
	global_store_dwordx4 v244, v[120:123], s[14:15]
	s_waitcnt vmcnt(15)
	v_lshlrev_b32_e32 v132, 16, v184
	v_and_b32_e32 v133, 0xffff0000, v184
	v_lshlrev_b32_e32 v134, 16, v185
	v_and_b32_e32 v135, 0xffff0000, v185
	v_lshlrev_b32_e32 v128, 16, v186
	v_and_b32_e32 v129, 0xffff0000, v186
	v_lshlrev_b32_e32 v130, 16, v187
	v_and_b32_e32 v131, 0xffff0000, v187
	v_pk_mul_f32 v[130:131], v[130:131], s[20:21] op_sel_hi:[1,0]
	v_pk_mul_f32 v[128:129], v[128:129], s[20:21] op_sel_hi:[1,0]
	v_pk_mul_f32 v[134:135], v[134:135], s[20:21] op_sel_hi:[1,0]
	v_pk_mul_f32 v[132:133], v[132:133], s[20:21] op_sel_hi:[1,0]
	v_pk_fma_f32 v[130:131], v[148:149], v[114:115], v[130:131]
	v_pk_fma_f32 v[114:115], v[150:151], v[112:113], v[128:129]
	v_pk_fma_f32 v[118:119], v[148:149], v[118:119], v[134:135]
	v_pk_fma_f32 v[116:117], v[150:151], v[116:117], v[132:133]
	v_cvt_pk_bf16_f32 v112, v116, v117
	v_cvt_pk_bf16_f32 v113, v118, v119
	v_cvt_pk_bf16_f32 v114, v114, v115
	v_cvt_pk_bf16_f32 v115, v130, v131
	global_store_dwordx4 v244, v[112:115], s[14:15] offset:256
	s_waitcnt vmcnt(15)
	v_lshlrev_b32_e32 v132, 16, v188
	v_and_b32_e32 v133, 0xffff0000, v188
	v_lshlrev_b32_e32 v134, 16, v189
	v_and_b32_e32 v135, 0xffff0000, v189
	v_lshlrev_b32_e32 v128, 16, v190
	v_and_b32_e32 v129, 0xffff0000, v190
	v_lshlrev_b32_e32 v130, 16, v191
	v_and_b32_e32 v131, 0xffff0000, v191
	v_add_u32_e32 v246, 0x8000, v245
	v_pk_mul_f32 v[130:131], v[130:131], s[20:21] op_sel_hi:[1,0]
	v_pk_mul_f32 v[128:129], v[128:129], s[20:21] op_sel_hi:[1,0]
	v_pk_mul_f32 v[134:135], v[134:135], s[20:21] op_sel_hi:[1,0]
	v_pk_mul_f32 v[132:133], v[132:133], s[20:21] op_sel_hi:[1,0]
	v_pk_fma_f32 v[130:131], v[148:149], v[106:107], v[130:131]
	v_pk_fma_f32 v[106:107], v[150:151], v[104:105], v[128:129]
	v_pk_fma_f32 v[110:111], v[148:149], v[110:111], v[134:135]
	v_pk_fma_f32 v[108:109], v[150:151], v[108:109], v[132:133]
	v_cvt_pk_bf16_f32 v104, v108, v109
	v_cvt_pk_bf16_f32 v105, v110, v111
	v_cvt_pk_bf16_f32 v106, v106, v107
	v_cvt_pk_bf16_f32 v107, v130, v131
	global_store_dwordx4 v246, v[104:107], s[14:15]
	s_waitcnt vmcnt(15)
	v_lshlrev_b32_e32 v132, 16, v192
	v_and_b32_e32 v133, 0xffff0000, v192
	v_lshlrev_b32_e32 v134, 16, v193
	v_and_b32_e32 v135, 0xffff0000, v193
	v_lshlrev_b32_e32 v128, 16, v194
	v_and_b32_e32 v129, 0xffff0000, v194
	v_lshlrev_b32_e32 v130, 16, v195
	v_and_b32_e32 v131, 0xffff0000, v195
	v_pk_mul_f32 v[130:131], v[130:131], s[20:21] op_sel_hi:[1,0]
	v_pk_mul_f32 v[128:129], v[128:129], s[20:21] op_sel_hi:[1,0]
	v_pk_mul_f32 v[134:135], v[134:135], s[20:21] op_sel_hi:[1,0]
	v_pk_mul_f32 v[132:133], v[132:133], s[20:21] op_sel_hi:[1,0]
	v_pk_fma_f32 v[130:131], v[148:149], v[98:99], v[130:131]
	v_pk_fma_f32 v[98:99], v[150:151], v[96:97], v[128:129]
	v_pk_fma_f32 v[102:103], v[148:149], v[102:103], v[134:135]
	v_pk_fma_f32 v[100:101], v[150:151], v[100:101], v[132:133]
	v_cvt_pk_bf16_f32 v96, v100, v101
	v_cvt_pk_bf16_f32 v97, v102, v103
	v_cvt_pk_bf16_f32 v98, v98, v99
	v_cvt_pk_bf16_f32 v99, v130, v131
	global_store_dwordx4 v246, v[96:99], s[14:15] offset:256
	s_waitcnt vmcnt(15)
; DI float bflo(unsigned w) { return __uint_as_float(w << 16); }
; DI float bfhi(unsigned w) { return __uint_as_float(w & 0xffff0000u); }
; DI unsigned cvt_pk_bf16(float lo, float hi) { unsigned r; asm volatile("v_cvt_pk_bf16_f32 %0, %1, %2" : "=v"(r) : "v"(lo), "v"(hi)); return r; }
;     DI void operator()(const f32x4 (&acc)[2][2][4][2], const pg8::Unit& u, int wr, int wc, int fr, int fq) const {
;     ...
;         for (int ai = 0; ai < 2; ++ai)
; #pragma unroll
;             for (int m = 0; m < 4; ++m) {
;                 const size_t off = (size_t)(row0 + ai * 128 + m * 16) * D_ + col0;
; #pragma unroll
;                 for (int bj = 0; bj < 2; ++bj) {
;                     const size_t o = off + bj * 128;
;                     f32x4 v0 = acc[ai][bj][m][0] * sc, v1 = acc[ai][bj][m][1] * sc;
;                     if (HAS_RES) {
;                         f32x4 r0, r1;
;                         if (resb) { const u32x4 rb = *(const u32x4*)(resb + o); r0 = (f32x4){bflo(rb.x), bfhi(rb.x), bflo(rb.y), bfhi(rb.y)}; r1 = (f32x4){bflo(rb.z), bfhi(rb.z), bflo(rb.w), bfhi(rb.w)}; }
;                         else { r0 = *(const f32x4*)(res + o); r1 = *(const f32x4*)(res + o + 4); }
;                         v0 = v0 + r0 * DN_ALPHA; v1 = v1 + r1 * DN_ALPHA;
;                     }
;                     u32x4 w; w.x = cvt_pk_bf16(v0[0], v0[1]); w.y = cvt_pk_bf16(v0[2], v0[3]); w.z = cvt_pk_bf16(v1[0], v1[1]); w.w = cvt_pk_bf16(v1[2], v1[3]);
;                     *(u32x4*)(out + o) = w;
;                 }
	v_lshlrev_b32_e32 v132, 16, v196
	v_and_b32_e32 v133, 0xffff0000, v196
	v_lshlrev_b32_e32 v134, 16, v197
	v_and_b32_e32 v135, 0xffff0000, v197
	v_lshlrev_b32_e32 v128, 16, v198
	v_and_b32_e32 v129, 0xffff0000, v198
	v_lshlrev_b32_e32 v130, 16, v199
	v_and_b32_e32 v131, 0xffff0000, v199
	v_add_u32_e32 v244, 0x10000, v245
	v_pk_mul_f32 v[130:131], v[130:131], s[20:21] op_sel_hi:[1,0]
	v_pk_mul_f32 v[128:129], v[128:129], s[20:21] op_sel_hi:[1,0]
	v_pk_mul_f32 v[134:135], v[134:135], s[20:21] op_sel_hi:[1,0]
	v_pk_mul_f32 v[132:133], v[132:133], s[20:21] op_sel_hi:[1,0]
	v_pk_fma_f32 v[130:131], v[148:149], v[90:91], v[130:131]
	v_pk_fma_f32 v[90:91], v[150:151], v[88:89], v[128:129]
	v_pk_fma_f32 v[94:95], v[148:149], v[94:95], v[134:135]
	v_pk_fma_f32 v[92:93], v[150:151], v[92:93], v[132:133]
	v_cvt_pk_bf16_f32 v88, v92, v93
	v_cvt_pk_bf16_f32 v89, v94, v95
	v_cvt_pk_bf16_f32 v90, v90, v91
	v_cvt_pk_bf16_f32 v91, v130, v131
	global_store_dwordx4 v244, v[88:91], s[14:15]
	s_waitcnt vmcnt(15)
	v_lshlrev_b32_e32 v132, 16, v200
	v_and_b32_e32 v133, 0xffff0000, v200
	v_lshlrev_b32_e32 v134, 16, v201
	v_and_b32_e32 v135, 0xffff0000, v201
	v_lshlrev_b32_e32 v128, 16, v202
	v_and_b32_e32 v129, 0xffff0000, v202
	v_lshlrev_b32_e32 v130, 16, v203
	v_and_b32_e32 v131, 0xffff0000, v203
	v_pk_mul_f32 v[130:131], v[130:131], s[20:21] op_sel_hi:[1,0]
	v_pk_mul_f32 v[128:129], v[128:129], s[20:21] op_sel_hi:[1,0]
	v_pk_mul_f32 v[134:135], v[134:135], s[20:21] op_sel_hi:[1,0]
	v_pk_mul_f32 v[132:133], v[132:133], s[20:21] op_sel_hi:[1,0]
	v_pk_fma_f32 v[130:131], v[148:149], v[82:83], v[130:131]
	v_pk_fma_f32 v[82:83], v[150:151], v[80:81], v[128:129]
	v_pk_fma_f32 v[86:87], v[148:149], v[86:87], v[134:135]
	v_pk_fma_f32 v[84:85], v[150:151], v[84:85], v[132:133]
	v_cvt_pk_bf16_f32 v80, v84, v85
	v_cvt_pk_bf16_f32 v81, v86, v87
	v_cvt_pk_bf16_f32 v82, v82, v83
	v_cvt_pk_bf16_f32 v83, v130, v131
	global_store_dwordx4 v244, v[80:83], s[14:15] offset:256
	s_waitcnt vmcnt(15)
	v_lshlrev_b32_e32 v132, 16, v204
	v_and_b32_e32 v133, 0xffff0000, v204
	v_lshlrev_b32_e32 v134, 16, v205
	v_and_b32_e32 v135, 0xffff0000, v205
	v_lshlrev_b32_e32 v128, 16, v206
	v_and_b32_e32 v129, 0xffff0000, v206
	v_lshlrev_b32_e32 v130, 16, v207
	v_and_b32_e32 v131, 0xffff0000, v207
	v_add_u32_e32 v246, 0x18000, v245
	v_pk_mul_f32 v[130:131], v[130:131], s[20:21] op_sel_hi:[1,0]
	v_pk_mul_f32 v[128:129], v[128:129], s[20:21] op_sel_hi:[1,0]
	v_pk_mul_f32 v[134:135], v[134:135], s[20:21] op_sel_hi:[1,0]
	v_pk_mul_f32 v[132:133], v[132:133], s[20:21] op_sel_hi:[1,0]
	v_pk_fma_f32 v[130:131], v[148:149], v[74:75], v[130:131]
	v_pk_fma_f32 v[74:75], v[150:151], v[72:73], v[128:129]
	v_pk_fma_f32 v[78:79], v[148:149], v[78:79], v[134:135]
	v_pk_fma_f32 v[76:77], v[150:151], v[76:77], v[132:133]
	v_cvt_pk_bf16_f32 v72, v76, v77
	v_cvt_pk_bf16_f32 v73, v78, v79
	v_cvt_pk_bf16_f32 v74, v74, v75
	v_cvt_pk_bf16_f32 v75, v130, v131
	global_store_dwordx4 v246, v[72:75], s[14:15]
	s_waitcnt vmcnt(15)
	v_lshlrev_b32_e32 v132, 16, v208
	v_and_b32_e32 v133, 0xffff0000, v208
	v_lshlrev_b32_e32 v134, 16, v209
	v_and_b32_e32 v135, 0xffff0000, v209
	v_lshlrev_b32_e32 v128, 16, v210
	v_and_b32_e32 v129, 0xffff0000, v210
	v_lshlrev_b32_e32 v130, 16, v211
	v_and_b32_e32 v131, 0xffff0000, v211
	v_pk_mul_f32 v[130:131], v[130:131], s[20:21] op_sel_hi:[1,0]
	v_pk_mul_f32 v[128:129], v[128:129], s[20:21] op_sel_hi:[1,0]
	v_pk_mul_f32 v[134:135], v[134:135], s[20:21] op_sel_hi:[1,0]
	v_pk_mul_f32 v[132:133], v[132:133], s[20:21] op_sel_hi:[1,0]
	v_pk_fma_f32 v[130:131], v[148:149], v[66:67], v[130:131]
	v_pk_fma_f32 v[66:67], v[150:151], v[64:65], v[128:129]
	v_pk_fma_f32 v[70:71], v[148:149], v[70:71], v[134:135]
	v_pk_fma_f32 v[68:69], v[150:151], v[68:69], v[132:133]
	v_cvt_pk_bf16_f32 v64, v68, v69
	v_cvt_pk_bf16_f32 v65, v70, v71
	v_cvt_pk_bf16_f32 v66, v66, v67
	v_cvt_pk_bf16_f32 v67, v130, v131
	global_store_dwordx4 v246, v[64:67], s[14:15] offset:256
	s_waitcnt vmcnt(15)
	v_lshlrev_b32_e32 v132, 16, v212
	v_and_b32_e32 v133, 0xffff0000, v212
	v_lshlrev_b32_e32 v134, 16, v213
	v_and_b32_e32 v135, 0xffff0000, v213
	v_lshlrev_b32_e32 v128, 16, v214
	v_and_b32_e32 v129, 0xffff0000, v214
	v_lshlrev_b32_e32 v130, 16, v215
	v_and_b32_e32 v131, 0xffff0000, v215
	v_add_u32_e32 v244, 0x40000, v245
	v_pk_mul_f32 v[130:131], v[130:131], s[20:21] op_sel_hi:[1,0]
	v_pk_mul_f32 v[128:129], v[128:129], s[20:21] op_sel_hi:[1,0]
	v_pk_mul_f32 v[134:135], v[134:135], s[20:21] op_sel_hi:[1,0]
	v_pk_mul_f32 v[132:133], v[132:133], s[20:21] op_sel_hi:[1,0]
	v_pk_fma_f32 v[130:131], v[148:149], v[58:59], v[130:131]
	v_pk_fma_f32 v[58:59], v[150:151], v[56:57], v[128:129]
	v_pk_fma_f32 v[62:63], v[148:149], v[62:63], v[134:135]
	v_pk_fma_f32 v[60:61], v[150:151], v[60:61], v[132:133]
	v_cvt_pk_bf16_f32 v56, v60, v61
	v_cvt_pk_bf16_f32 v57, v62, v63
	v_cvt_pk_bf16_f32 v58, v58, v59
	v_cvt_pk_bf16_f32 v59, v130, v131
	global_store_dwordx4 v244, v[56:59], s[14:15]
	s_waitcnt vmcnt(15)
	v_lshlrev_b32_e32 v132, 16, v216
	v_and_b32_e32 v133, 0xffff0000, v216
	v_lshlrev_b32_e32 v134, 16, v217
	v_and_b32_e32 v135, 0xffff0000, v217
	v_lshlrev_b32_e32 v128, 16, v218
	v_and_b32_e32 v129, 0xffff0000, v218
	v_lshlrev_b32_e32 v130, 16, v219
	v_and_b32_e32 v131, 0xffff0000, v219
	v_pk_mul_f32 v[130:131], v[130:131], s[20:21] op_sel_hi:[1,0]
	v_pk_mul_f32 v[128:129], v[128:129], s[20:21] op_sel_hi:[1,0]
	v_pk_mul_f32 v[134:135], v[134:135], s[20:21] op_sel_hi:[1,0]
	v_pk_mul_f32 v[132:133], v[132:133], s[20:21] op_sel_hi:[1,0]
	v_pk_fma_f32 v[130:131], v[148:149], v[50:51], v[130:131]
	v_pk_fma_f32 v[50:51], v[150:151], v[48:49], v[128:129]
	v_pk_fma_f32 v[54:55], v[148:149], v[54:55], v[134:135]
	v_pk_fma_f32 v[52:53], v[150:151], v[52:53], v[132:133]
	v_cvt_pk_bf16_f32 v48, v52, v53
	v_cvt_pk_bf16_f32 v49, v54, v55
	v_cvt_pk_bf16_f32 v50, v50, v51
	v_cvt_pk_bf16_f32 v51, v130, v131
	global_store_dwordx4 v244, v[48:51], s[14:15] offset:256
	s_waitcnt vmcnt(15)
; DI float bflo(unsigned w) { return __uint_as_float(w << 16); }
; DI float bfhi(unsigned w) { return __uint_as_float(w & 0xffff0000u); }
; DI unsigned cvt_pk_bf16(float lo, float hi) { unsigned r; asm volatile("v_cvt_pk_bf16_f32 %0, %1, %2" : "=v"(r) : "v"(lo), "v"(hi)); return r; }
;     DI void operator()(const f32x4 (&acc)[2][2][4][2], const pg8::Unit& u, int wr, int wc, int fr, int fq) const {
;     ...
;         for (int ai = 0; ai < 2; ++ai)
; #pragma unroll
;             for (int m = 0; m < 4; ++m) {
;                 const size_t off = (size_t)(row0 + ai * 128 + m * 16) * D_ + col0;
; #pragma unroll
;                 for (int bj = 0; bj < 2; ++bj) {
;                     const size_t o = off + bj * 128;
;                     f32x4 v0 = acc[ai][bj][m][0] * sc, v1 = acc[ai][bj][m][1] * sc;
;                     if (HAS_RES) {
;                         f32x4 r0, r1;
;                         if (resb) { const u32x4 rb = *(const u32x4*)(resb + o); r0 = (f32x4){bflo(rb.x), bfhi(rb.x), bflo(rb.y), bfhi(rb.y)}; r1 = (f32x4){bflo(rb.z), bfhi(rb.z), bflo(rb.w), bfhi(rb.w)}; }
;                         else { r0 = *(const f32x4*)(res + o); r1 = *(const f32x4*)(res + o + 4); }
;                         v0 = v0 + r0 * DN_ALPHA; v1 = v1 + r1 * DN_ALPHA;
;                     }
;                     u32x4 w; w.x = cvt_pk_bf16(v0[0], v0[1]); w.y = cvt_pk_bf16(v0[2], v0[3]); w.z = cvt_pk_bf16(v1[0], v1[1]); w.w = cvt_pk_bf16(v1[2], v1[3]);
;                     *(u32x4*)(out + o) = w;
;                 }
	v_lshlrev_b32_e32 v132, 16, v220
	v_and_b32_e32 v133, 0xffff0000, v220
	v_lshlrev_b32_e32 v134, 16, v221
	v_and_b32_e32 v135, 0xffff0000, v221
	v_lshlrev_b32_e32 v128, 16, v222
	v_and_b32_e32 v129, 0xffff0000, v222
	v_lshlrev_b32_e32 v130, 16, v223
	v_and_b32_e32 v131, 0xffff0000, v223
	v_add_u32_e32 v246, 0x48000, v245
	v_pk_mul_f32 v[130:131], v[130:131], s[20:21] op_sel_hi:[1,0]
	v_pk_mul_f32 v[128:129], v[128:129], s[20:21] op_sel_hi:[1,0]
	v_pk_mul_f32 v[134:135], v[134:135], s[20:21] op_sel_hi:[1,0]
	v_pk_mul_f32 v[132:133], v[132:133], s[20:21] op_sel_hi:[1,0]
	v_pk_fma_f32 v[130:131], v[148:149], v[42:43], v[130:131]
	v_pk_fma_f32 v[42:43], v[150:151], v[40:41], v[128:129]
	v_pk_fma_f32 v[46:47], v[148:149], v[46:47], v[134:135]
	v_pk_fma_f32 v[44:45], v[150:151], v[44:45], v[132:133]
	v_cvt_pk_bf16_f32 v40, v44, v45
	v_cvt_pk_bf16_f32 v41, v46, v47
	v_cvt_pk_bf16_f32 v42, v42, v43
	v_cvt_pk_bf16_f32 v43, v130, v131
	global_store_dwordx4 v246, v[40:43], s[14:15]
	s_waitcnt vmcnt(15)
	v_lshlrev_b32_e32 v132, 16, v224
	v_and_b32_e32 v133, 0xffff0000, v224
	v_lshlrev_b32_e32 v134, 16, v225
	v_and_b32_e32 v135, 0xffff0000, v225
	v_lshlrev_b32_e32 v128, 16, v226
	v_and_b32_e32 v129, 0xffff0000, v226
	v_lshlrev_b32_e32 v130, 16, v227
	v_and_b32_e32 v131, 0xffff0000, v227
	v_pk_mul_f32 v[130:131], v[130:131], s[20:21] op_sel_hi:[1,0]
	v_pk_mul_f32 v[128:129], v[128:129], s[20:21] op_sel_hi:[1,0]
	v_pk_mul_f32 v[134:135], v[134:135], s[20:21] op_sel_hi:[1,0]
	v_pk_mul_f32 v[132:133], v[132:133], s[20:21] op_sel_hi:[1,0]
	v_pk_fma_f32 v[130:131], v[148:149], v[34:35], v[130:131]
	v_pk_fma_f32 v[34:35], v[150:151], v[32:33], v[128:129]
	v_pk_fma_f32 v[38:39], v[148:149], v[38:39], v[134:135]
	v_pk_fma_f32 v[36:37], v[150:151], v[36:37], v[132:133]
	v_cvt_pk_bf16_f32 v32, v36, v37
	v_cvt_pk_bf16_f32 v33, v38, v39
	v_cvt_pk_bf16_f32 v34, v34, v35
	v_cvt_pk_bf16_f32 v35, v130, v131
	global_store_dwordx4 v246, v[32:35], s[14:15] offset:256
	s_waitcnt vmcnt(15)
	v_lshlrev_b32_e32 v132, 16, v228
	v_and_b32_e32 v133, 0xffff0000, v228
	v_lshlrev_b32_e32 v134, 16, v229
	v_and_b32_e32 v135, 0xffff0000, v229
	v_lshlrev_b32_e32 v128, 16, v230
	v_and_b32_e32 v129, 0xffff0000, v230
	v_lshlrev_b32_e32 v130, 16, v231
	v_and_b32_e32 v131, 0xffff0000, v231
	v_add_u32_e32 v244, 0x50000, v245
	v_pk_mul_f32 v[130:131], v[130:131], s[20:21] op_sel_hi:[1,0]
	v_pk_mul_f32 v[128:129], v[128:129], s[20:21] op_sel_hi:[1,0]
	v_pk_mul_f32 v[134:135], v[134:135], s[20:21] op_sel_hi:[1,0]
	v_pk_mul_f32 v[132:133], v[132:133], s[20:21] op_sel_hi:[1,0]
	v_pk_fma_f32 v[130:131], v[148:149], v[26:27], v[130:131]
	v_pk_fma_f32 v[26:27], v[150:151], v[24:25], v[128:129]
	v_pk_fma_f32 v[30:31], v[148:149], v[30:31], v[134:135]
	v_pk_fma_f32 v[28:29], v[150:151], v[28:29], v[132:133]
	v_cvt_pk_bf16_f32 v24, v28, v29
	v_cvt_pk_bf16_f32 v25, v30, v31
	v_cvt_pk_bf16_f32 v26, v26, v27
	v_cvt_pk_bf16_f32 v27, v130, v131
	global_store_dwordx4 v244, v[24:27], s[14:15]
	s_waitcnt vmcnt(15)
	v_lshlrev_b32_e32 v132, 16, v232
	v_and_b32_e32 v133, 0xffff0000, v232
	v_lshlrev_b32_e32 v134, 16, v233
	v_and_b32_e32 v135, 0xffff0000, v233
	v_lshlrev_b32_e32 v128, 16, v234
	v_and_b32_e32 v129, 0xffff0000, v234
	v_lshlrev_b32_e32 v130, 16, v235
	v_and_b32_e32 v131, 0xffff0000, v235
	v_pk_mul_f32 v[130:131], v[130:131], s[20:21] op_sel_hi:[1,0]
	v_pk_mul_f32 v[128:129], v[128:129], s[20:21] op_sel_hi:[1,0]
	v_pk_mul_f32 v[134:135], v[134:135], s[20:21] op_sel_hi:[1,0]
	v_pk_mul_f32 v[132:133], v[132:133], s[20:21] op_sel_hi:[1,0]
	v_pk_fma_f32 v[130:131], v[148:149], v[18:19], v[130:131]
	v_pk_fma_f32 v[18:19], v[150:151], v[16:17], v[128:129]
	v_pk_fma_f32 v[22:23], v[148:149], v[22:23], v[134:135]
	v_pk_fma_f32 v[20:21], v[150:151], v[20:21], v[132:133]
	v_cvt_pk_bf16_f32 v16, v20, v21
	v_cvt_pk_bf16_f32 v17, v22, v23
	v_cvt_pk_bf16_f32 v18, v18, v19
	v_cvt_pk_bf16_f32 v19, v130, v131
	global_store_dwordx4 v244, v[16:19], s[14:15] offset:256
	s_waitcnt vmcnt(15)
	v_lshlrev_b32_e32 v132, 16, v236
	v_and_b32_e32 v133, 0xffff0000, v236
	v_lshlrev_b32_e32 v134, 16, v237
	v_and_b32_e32 v135, 0xffff0000, v237
	v_lshlrev_b32_e32 v128, 16, v238
	v_and_b32_e32 v129, 0xffff0000, v238
	v_lshlrev_b32_e32 v130, 16, v239
	v_and_b32_e32 v131, 0xffff0000, v239
	v_add_u32_e32 v246, 0x58000, v245
	v_pk_mul_f32 v[130:131], v[130:131], s[20:21] op_sel_hi:[1,0]
	v_pk_mul_f32 v[128:129], v[128:129], s[20:21] op_sel_hi:[1,0]
	v_pk_mul_f32 v[134:135], v[134:135], s[20:21] op_sel_hi:[1,0]
	v_pk_mul_f32 v[132:133], v[132:133], s[20:21] op_sel_hi:[1,0]
	v_pk_fma_f32 v[130:131], v[148:149], v[10:11], v[130:131]
	v_pk_fma_f32 v[10:11], v[150:151], v[8:9], v[128:129]
	v_pk_fma_f32 v[14:15], v[148:149], v[14:15], v[134:135]
	v_pk_fma_f32 v[12:13], v[150:151], v[12:13], v[132:133]
	v_cvt_pk_bf16_f32 v8, v12, v13
	v_cvt_pk_bf16_f32 v9, v14, v15
	v_cvt_pk_bf16_f32 v10, v10, v11
	v_cvt_pk_bf16_f32 v11, v130, v131
	global_store_dwordx4 v246, v[8:11], s[14:15]
	s_waitcnt vmcnt(15)
	v_lshlrev_b32_e32 v132, 16, v240
	v_and_b32_e32 v133, 0xffff0000, v240
	v_lshlrev_b32_e32 v134, 16, v241
	v_and_b32_e32 v135, 0xffff0000, v241
	v_lshlrev_b32_e32 v128, 16, v242
	v_and_b32_e32 v129, 0xffff0000, v242
	v_lshlrev_b32_e32 v130, 16, v243
	v_and_b32_e32 v131, 0xffff0000, v243
	v_pk_mul_f32 v[130:131], v[130:131], s[20:21] op_sel_hi:[1,0]
	v_pk_mul_f32 v[128:129], v[128:129], s[20:21] op_sel_hi:[1,0]
	v_pk_mul_f32 v[134:135], v[134:135], s[20:21] op_sel_hi:[1,0]
	v_pk_mul_f32 v[132:133], v[132:133], s[20:21] op_sel_hi:[1,0]
	v_pk_fma_f32 v[130:131], v[148:149], v[2:3], v[130:131]
	v_pk_fma_f32 v[2:3], v[150:151], v[0:1], v[128:129]
	v_pk_fma_f32 v[6:7], v[148:149], v[6:7], v[134:135]
	v_pk_fma_f32 v[4:5], v[150:151], v[4:5], v[132:133]
	v_cvt_pk_bf16_f32 v0, v4, v5
	v_cvt_pk_bf16_f32 v1, v6, v7
	v_cvt_pk_bf16_f32 v2, v2, v3
	v_cvt_pk_bf16_f32 v3, v130, v131
	global_store_dwordx4 v246, v[0:3], s[14:15] offset:256
	s_branch .Lepr_done
; DI float bflo(unsigned w) { return __uint_as_float(w << 16); }
; DI float bfhi(unsigned w) { return __uint_as_float(w & 0xffff0000u); }
; DI unsigned cvt_pk_bf16(float lo, float hi) { unsigned r; asm volatile("v_cvt_pk_bf16_f32 %0, %1, %2" : "=v"(r) : "v"(lo), "v"(hi)); return r; }
;     DI void operator()(const f32x4 (&acc)[2][2][4][2], const pg8::Unit& u, int wr, int wc, int fr, int fq) const {
;     ...
;         for (int ai = 0; ai < 2; ++ai)
; #pragma unroll
;             for (int m = 0; m < 4; ++m) {
;                 const size_t off = (size_t)(row0 + ai * 128 + m * 16) * D_ + col0;
; #pragma unroll
;                 for (int bj = 0; bj < 2; ++bj) {
;                     const size_t o = off + bj * 128;
;                     f32x4 v0 = acc[ai][bj][m][0] * sc, v1 = acc[ai][bj][m][1] * sc;
;                     if (HAS_RES) {
;                         f32x4 r0, r1;
;                         if (resb) { const u32x4 rb = *(const u32x4*)(resb + o); r0 = (f32x4){bflo(rb.x), bfhi(rb.x), bflo(rb.y), bfhi(rb.y)}; r1 = (f32x4){bflo(rb.z), bfhi(rb.z), bflo(rb.w), bfhi(rb.w)}; }
;                         else { r0 = *(const f32x4*)(res + o); r1 = *(const f32x4*)(res + o + 4); }
;                         v0 = v0 + r0 * DN_ALPHA; v1 = v1 + r1 * DN_ALPHA;
;                     }
;                     u32x4 w; w.x = cvt_pk_bf16(v0[0], v0[1]); w.y = cvt_pk_bf16(v0[2], v0[3]); w.z = cvt_pk_bf16(v1[0], v1[1]); w.w = cvt_pk_bf16(v1[2], v1[3]);
;                     *(u32x4*)(out + o) = w;
;                 }
.Lepr_f32:
	v_lshlrev_b32_e32 v247, 2, v160
	v_mov_b32_e32 v244, v247
	global_load_dwordx4 v[180:183], v244, s[16:17] offset:16
	global_load_dwordx4 v[184:187], v244, s[16:17]
	global_load_dwordx4 v[188:191], v244, s[16:17] offset:528
	global_load_dwordx4 v[192:195], v244, s[16:17] offset:512
	v_add_u32_e32 v246, 0x10000, v247
	global_load_dwordx4 v[196:199], v246, s[16:17] offset:16
	global_load_dwordx4 v[200:203], v246, s[16:17]
	global_load_dwordx4 v[204:207], v246, s[16:17] offset:528
	global_load_dwordx4 v[208:211], v246, s[16:17] offset:512
	v_add_u32_e32 v244, 0x20000, v247
	global_load_dwordx4 v[212:215], v244, s[16:17] offset:16
	global_load_dwordx4 v[216:219], v244, s[16:17]
	global_load_dwordx4 v[220:223], v244, s[16:17] offset:528
	global_load_dwordx4 v[224:227], v244, s[16:17] offset:512
	v_add_u32_e32 v246, 0x30000, v247
	global_load_dwordx4 v[228:231], v246, s[16:17] offset:16
	global_load_dwordx4 v[232:235], v246, s[16:17]
	global_load_dwordx4 v[236:239], v246, s[16:17] offset:528
	global_load_dwordx4 v[240:243], v246, s[16:17] offset:512
	s_waitcnt vmcnt(14)
	v_mov_b32_e32 v128, v245
	v_pk_mul_f32 v[182:183], v[182:183], s[20:21] op_sel_hi:[1,0]
	v_pk_mul_f32 v[180:181], v[180:181], s[20:21] op_sel_hi:[1,0]
	v_pk_mul_f32 v[186:187], v[186:187], s[20:21] op_sel_hi:[1,0]
	v_pk_mul_f32 v[184:185], v[184:185], s[20:21] op_sel_hi:[1,0]
	v_pk_fma_f32 v[182:183], v[148:149], v[122:123], v[182:183]
	v_pk_fma_f32 v[122:123], v[150:151], v[120:121], v[180:181]
	v_pk_fma_f32 v[126:127], v[148:149], v[126:127], v[186:187]
	v_pk_fma_f32 v[124:125], v[150:151], v[124:125], v[184:185]
	v_cvt_pk_bf16_f32 v120, v124, v125
	v_cvt_pk_bf16_f32 v121, v126, v127
	v_cvt_pk_bf16_f32 v122, v122, v123
	v_cvt_pk_bf16_f32 v123, v182, v183
	global_store_dwordx4 v128, v[120:123], s[14:15]
	v_add_u32_e32 v244, 0x80000, v247
	global_load_dwordx4 v[180:183], v244, s[16:17] offset:16
	global_load_dwordx4 v[184:187], v244, s[16:17]
	s_waitcnt vmcnt(15)
	v_pk_mul_f32 v[190:191], v[190:191], s[20:21] op_sel_hi:[1,0]
	v_pk_mul_f32 v[188:189], v[188:189], s[20:21] op_sel_hi:[1,0]
	v_pk_mul_f32 v[194:195], v[194:195], s[20:21] op_sel_hi:[1,0]
	v_pk_mul_f32 v[192:193], v[192:193], s[20:21] op_sel_hi:[1,0]
	v_pk_fma_f32 v[190:191], v[148:149], v[114:115], v[190:191]
	v_pk_fma_f32 v[114:115], v[150:151], v[112:113], v[188:189]
	v_pk_fma_f32 v[118:119], v[148:149], v[118:119], v[194:195]
	v_pk_fma_f32 v[116:117], v[150:151], v[116:117], v[192:193]
	v_cvt_pk_bf16_f32 v112, v116, v117
	v_cvt_pk_bf16_f32 v113, v118, v119
	v_cvt_pk_bf16_f32 v114, v114, v115
	v_cvt_pk_bf16_f32 v115, v190, v191
	global_store_dwordx4 v128, v[112:115], s[14:15] offset:256
	global_load_dwordx4 v[188:191], v244, s[16:17] offset:528
	global_load_dwordx4 v[192:195], v244, s[16:17] offset:512
	s_waitcnt vmcnt(16)
	v_add_u32_e32 v129, 0x8000, v245
	v_pk_mul_f32 v[198:199], v[198:199], s[20:21] op_sel_hi:[1,0]
	v_pk_mul_f32 v[196:197], v[196:197], s[20:21] op_sel_hi:[1,0]
	v_pk_mul_f32 v[202:203], v[202:203], s[20:21] op_sel_hi:[1,0]
	v_pk_mul_f32 v[200:201], v[200:201], s[20:21] op_sel_hi:[1,0]
	v_pk_fma_f32 v[198:199], v[148:149], v[106:107], v[198:199]
	v_pk_fma_f32 v[106:107], v[150:151], v[104:105], v[196:197]
	v_pk_fma_f32 v[110:111], v[148:149], v[110:111], v[202:203]
	v_pk_fma_f32 v[108:109], v[150:151], v[108:109], v[200:201]
	v_cvt_pk_bf16_f32 v104, v108, v109
	v_cvt_pk_bf16_f32 v105, v110, v111
	v_cvt_pk_bf16_f32 v106, v106, v107
	v_cvt_pk_bf16_f32 v107, v198, v199
	global_store_dwordx4 v129, v[104:107], s[14:15]
	v_add_u32_e32 v246, 0x90000, v247
	global_load_dwordx4 v[196:199], v246, s[16:17] offset:16
	global_load_dwordx4 v[200:203], v246, s[16:17]
	s_waitcnt vmcnt(17)
	v_pk_mul_f32 v[206:207], v[206:207], s[20:21] op_sel_hi:[1,0]
	v_pk_mul_f32 v[204:205], v[204:205], s[20:21] op_sel_hi:[1,0]
	v_pk_mul_f32 v[210:211], v[210:211], s[20:21] op_sel_hi:[1,0]
	v_pk_mul_f32 v[208:209], v[208:209], s[20:21] op_sel_hi:[1,0]
	v_pk_fma_f32 v[206:207], v[148:149], v[98:99], v[206:207]
	v_pk_fma_f32 v[98:99], v[150:151], v[96:97], v[204:205]
	v_pk_fma_f32 v[102:103], v[148:149], v[102:103], v[210:211]
	v_pk_fma_f32 v[100:101], v[150:151], v[100:101], v[208:209]
	v_cvt_pk_bf16_f32 v96, v100, v101
	v_cvt_pk_bf16_f32 v97, v102, v103
	v_cvt_pk_bf16_f32 v98, v98, v99
	v_cvt_pk_bf16_f32 v99, v206, v207
	global_store_dwordx4 v129, v[96:99], s[14:15] offset:256
	global_load_dwordx4 v[204:207], v246, s[16:17] offset:528
	global_load_dwordx4 v[208:211], v246, s[16:17] offset:512
	s_waitcnt vmcnt(18)
	v_add_u32_e32 v128, 0x10000, v245
	v_pk_mul_f32 v[214:215], v[214:215], s[20:21] op_sel_hi:[1,0]
	v_pk_mul_f32 v[212:213], v[212:213], s[20:21] op_sel_hi:[1,0]
	v_pk_mul_f32 v[218:219], v[218:219], s[20:21] op_sel_hi:[1,0]
	v_pk_mul_f32 v[216:217], v[216:217], s[20:21] op_sel_hi:[1,0]
	v_pk_fma_f32 v[214:215], v[148:149], v[90:91], v[214:215]
	v_pk_fma_f32 v[90:91], v[150:151], v[88:89], v[212:213]
	v_pk_fma_f32 v[94:95], v[148:149], v[94:95], v[218:219]
	v_pk_fma_f32 v[92:93], v[150:151], v[92:93], v[216:217]
	v_cvt_pk_bf16_f32 v88, v92, v93
	v_cvt_pk_bf16_f32 v89, v94, v95
	v_cvt_pk_bf16_f32 v90, v90, v91
	v_cvt_pk_bf16_f32 v91, v214, v215
	global_store_dwordx4 v128, v[88:91], s[14:15]
	v_add_u32_e32 v244, 0xa0000, v247
	global_load_dwordx4 v[212:215], v244, s[16:17] offset:16
	global_load_dwordx4 v[216:219], v244, s[16:17]
	s_waitcnt vmcnt(19)
; DI float bflo(unsigned w) { return __uint_as_float(w << 16); }
; DI float bfhi(unsigned w) { return __uint_as_float(w & 0xffff0000u); }
; DI unsigned cvt_pk_bf16(float lo, float hi) { unsigned r; asm volatile("v_cvt_pk_bf16_f32 %0, %1, %2" : "=v"(r) : "v"(lo), "v"(hi)); return r; }
;     DI void operator()(const f32x4 (&acc)[2][2][4][2], const pg8::Unit& u, int wr, int wc, int fr, int fq) const {
;     ...
;         for (int ai = 0; ai < 2; ++ai)
; #pragma unroll
;             for (int m = 0; m < 4; ++m) {
;                 const size_t off = (size_t)(row0 + ai * 128 + m * 16) * D_ + col0;
; #pragma unroll
;                 for (int bj = 0; bj < 2; ++bj) {
;                     const size_t o = off + bj * 128;
;                     f32x4 v0 = acc[ai][bj][m][0] * sc, v1 = acc[ai][bj][m][1] * sc;
;                     if (HAS_RES) {
;                         f32x4 r0, r1;
;                         if (resb) { const u32x4 rb = *(const u32x4*)(resb + o); r0 = (f32x4){bflo(rb.x), bfhi(rb.x), bflo(rb.y), bfhi(rb.y)}; r1 = (f32x4){bflo(rb.z), bfhi(rb.z), bflo(rb.w), bfhi(rb.w)}; }
;                         else { r0 = *(const f32x4*)(res + o); r1 = *(const f32x4*)(res + o + 4); }
;                         v0 = v0 + r0 * DN_ALPHA; v1 = v1 + r1 * DN_ALPHA;
;                     }
;                     u32x4 w; w.x = cvt_pk_bf16(v0[0], v0[1]); w.y = cvt_pk_bf16(v0[2], v0[3]); w.z = cvt_pk_bf16(v1[0], v1[1]); w.w = cvt_pk_bf16(v1[2], v1[3]);
;                     *(u32x4*)(out + o) = w;
;                 }
	v_pk_mul_f32 v[222:223], v[222:223], s[20:21] op_sel_hi:[1,0]
	v_pk_mul_f32 v[220:221], v[220:221], s[20:21] op_sel_hi:[1,0]
	v_pk_mul_f32 v[226:227], v[226:227], s[20:21] op_sel_hi:[1,0]
	v_pk_mul_f32 v[224:225], v[224:225], s[20:21] op_sel_hi:[1,0]
	v_pk_fma_f32 v[222:223], v[148:149], v[82:83], v[222:223]
	v_pk_fma_f32 v[82:83], v[150:151], v[80:81], v[220:221]
	v_pk_fma_f32 v[86:87], v[148:149], v[86:87], v[226:227]
	v_pk_fma_f32 v[84:85], v[150:151], v[84:85], v[224:225]
	v_cvt_pk_bf16_f32 v80, v84, v85
	v_cvt_pk_bf16_f32 v81, v86, v87
	v_cvt_pk_bf16_f32 v82, v82, v83
	v_cvt_pk_bf16_f32 v83, v222, v223
	global_store_dwordx4 v128, v[80:83], s[14:15] offset:256
	global_load_dwordx4 v[220:223], v244, s[16:17] offset:528
	global_load_dwordx4 v[224:227], v244, s[16:17] offset:512
	s_waitcnt vmcnt(20)
	v_add_u32_e32 v129, 0x18000, v245
	v_pk_mul_f32 v[230:231], v[230:231], s[20:21] op_sel_hi:[1,0]
	v_pk_mul_f32 v[228:229], v[228:229], s[20:21] op_sel_hi:[1,0]
	v_pk_mul_f32 v[234:235], v[234:235], s[20:21] op_sel_hi:[1,0]
	v_pk_mul_f32 v[232:233], v[232:233], s[20:21] op_sel_hi:[1,0]
	v_pk_fma_f32 v[230:231], v[148:149], v[74:75], v[230:231]
	v_pk_fma_f32 v[74:75], v[150:151], v[72:73], v[228:229]
	v_pk_fma_f32 v[78:79], v[148:149], v[78:79], v[234:235]
	v_pk_fma_f32 v[76:77], v[150:151], v[76:77], v[232:233]
	v_cvt_pk_bf16_f32 v72, v76, v77
	v_cvt_pk_bf16_f32 v73, v78, v79
	v_cvt_pk_bf16_f32 v74, v74, v75
	v_cvt_pk_bf16_f32 v75, v230, v231
	global_store_dwordx4 v129, v[72:75], s[14:15]
	v_add_u32_e32 v246, 0xb0000, v247
	global_load_dwordx4 v[228:231], v246, s[16:17] offset:16
	global_load_dwordx4 v[232:235], v246, s[16:17]
	s_waitcnt vmcnt(21)
	v_pk_mul_f32 v[238:239], v[238:239], s[20:21] op_sel_hi:[1,0]
	v_pk_mul_f32 v[236:237], v[236:237], s[20:21] op_sel_hi:[1,0]
	v_pk_mul_f32 v[242:243], v[242:243], s[20:21] op_sel_hi:[1,0]
	v_pk_mul_f32 v[240:241], v[240:241], s[20:21] op_sel_hi:[1,0]
	v_pk_fma_f32 v[238:239], v[148:149], v[66:67], v[238:239]
	v_pk_fma_f32 v[66:67], v[150:151], v[64:65], v[236:237]
	v_pk_fma_f32 v[70:71], v[148:149], v[70:71], v[242:243]
	v_pk_fma_f32 v[68:69], v[150:151], v[68:69], v[240:241]
	v_cvt_pk_bf16_f32 v64, v68, v69
	v_cvt_pk_bf16_f32 v65, v70, v71
	v_cvt_pk_bf16_f32 v66, v66, v67
	v_cvt_pk_bf16_f32 v67, v238, v239
	global_store_dwordx4 v129, v[64:67], s[14:15] offset:256
	global_load_dwordx4 v[236:239], v246, s[16:17] offset:528
	global_load_dwordx4 v[240:243], v246, s[16:17] offset:512
	s_waitcnt vmcnt(21)
	v_add_u32_e32 v128, 0x40000, v245
	v_pk_mul_f32 v[182:183], v[182:183], s[20:21] op_sel_hi:[1,0]
	v_pk_mul_f32 v[180:181], v[180:181], s[20:21] op_sel_hi:[1,0]
	v_pk_mul_f32 v[186:187], v[186:187], s[20:21] op_sel_hi:[1,0]
	v_pk_mul_f32 v[184:185], v[184:185], s[20:21] op_sel_hi:[1,0]
	v_pk_fma_f32 v[182:183], v[148:149], v[58:59], v[182:183]
	v_pk_fma_f32 v[58:59], v[150:151], v[56:57], v[180:181]
	v_pk_fma_f32 v[62:63], v[148:149], v[62:63], v[186:187]
	v_pk_fma_f32 v[60:61], v[150:151], v[60:61], v[184:185]
	v_cvt_pk_bf16_f32 v56, v60, v61
	v_cvt_pk_bf16_f32 v57, v62, v63
	v_cvt_pk_bf16_f32 v58, v58, v59
	v_cvt_pk_bf16_f32 v59, v182, v183
	global_store_dwordx4 v128, v[56:59], s[14:15]
	s_waitcnt vmcnt(19)
	v_pk_mul_f32 v[190:191], v[190:191], s[20:21] op_sel_hi:[1,0]
	v_pk_mul_f32 v[188:189], v[188:189], s[20:21] op_sel_hi:[1,0]
	v_pk_mul_f32 v[194:195], v[194:195], s[20:21] op_sel_hi:[1,0]
	v_pk_mul_f32 v[192:193], v[192:193], s[20:21] op_sel_hi:[1,0]
	v_pk_fma_f32 v[190:191], v[148:149], v[50:51], v[190:191]
	v_pk_fma_f32 v[50:51], v[150:151], v[48:49], v[188:189]
	v_pk_fma_f32 v[54:55], v[148:149], v[54:55], v[194:195]
	v_pk_fma_f32 v[52:53], v[150:151], v[52:53], v[192:193]
	v_cvt_pk_bf16_f32 v48, v52, v53
	v_cvt_pk_bf16_f32 v49, v54, v55
	v_cvt_pk_bf16_f32 v50, v50, v51
	v_cvt_pk_bf16_f32 v51, v190, v191
	global_store_dwordx4 v128, v[48:51], s[14:15] offset:256
	s_waitcnt vmcnt(17)
; DI float bflo(unsigned w) { return __uint_as_float(w << 16); }
; DI float bfhi(unsigned w) { return __uint_as_float(w & 0xffff0000u); }
; DI unsigned cvt_pk_bf16(float lo, float hi) { unsigned r; asm volatile("v_cvt_pk_bf16_f32 %0, %1, %2" : "=v"(r) : "v"(lo), "v"(hi)); return r; }
;     DI void operator()(const f32x4 (&acc)[2][2][4][2], const pg8::Unit& u, int wr, int wc, int fr, int fq) const {
;     ...
;         for (int ai = 0; ai < 2; ++ai)
; #pragma unroll
;             for (int m = 0; m < 4; ++m) {
;                 const size_t off = (size_t)(row0 + ai * 128 + m * 16) * D_ + col0;
; #pragma unroll
;                 for (int bj = 0; bj < 2; ++bj) {
;                     const size_t o = off + bj * 128;
;                     f32x4 v0 = acc[ai][bj][m][0] * sc, v1 = acc[ai][bj][m][1] * sc;
;                     if (HAS_RES) {
;                         f32x4 r0, r1;
;                         if (resb) { const u32x4 rb = *(const u32x4*)(resb + o); r0 = (f32x4){bflo(rb.x), bfhi(rb.x), bflo(rb.y), bfhi(rb.y)}; r1 = (f32x4){bflo(rb.z), bfhi(rb.z), bflo(rb.w), bfhi(rb.w)}; }
;                         else { r0 = *(const f32x4*)(res + o); r1 = *(const f32x4*)(res + o + 4); }
;                         v0 = v0 + r0 * DN_ALPHA; v1 = v1 + r1 * DN_ALPHA;
;                     }
;                     u32x4 w; w.x = cvt_pk_bf16(v0[0], v0[1]); w.y = cvt_pk_bf16(v0[2], v0[3]); w.z = cvt_pk_bf16(v1[0], v1[1]); w.w = cvt_pk_bf16(v1[2], v1[3]);
;                     *(u32x4*)(out + o) = w;
;                 }
	v_add_u32_e32 v129, 0x48000, v245
	v_pk_mul_f32 v[198:199], v[198:199], s[20:21] op_sel_hi:[1,0]
	v_pk_mul_f32 v[196:197], v[196:197], s[20:21] op_sel_hi:[1,0]
	v_pk_mul_f32 v[202:203], v[202:203], s[20:21] op_sel_hi:[1,0]
	v_pk_mul_f32 v[200:201], v[200:201], s[20:21] op_sel_hi:[1,0]
	v_pk_fma_f32 v[198:199], v[148:149], v[42:43], v[198:199]
	v_pk_fma_f32 v[42:43], v[150:151], v[40:41], v[196:197]
	v_pk_fma_f32 v[46:47], v[148:149], v[46:47], v[202:203]
	v_pk_fma_f32 v[44:45], v[150:151], v[44:45], v[200:201]
	v_cvt_pk_bf16_f32 v40, v44, v45
	v_cvt_pk_bf16_f32 v41, v46, v47
	v_cvt_pk_bf16_f32 v42, v42, v43
	v_cvt_pk_bf16_f32 v43, v198, v199
	global_store_dwordx4 v129, v[40:43], s[14:15]
	s_waitcnt vmcnt(15)
	v_pk_mul_f32 v[206:207], v[206:207], s[20:21] op_sel_hi:[1,0]
	v_pk_mul_f32 v[204:205], v[204:205], s[20:21] op_sel_hi:[1,0]
	v_pk_mul_f32 v[210:211], v[210:211], s[20:21] op_sel_hi:[1,0]
	v_pk_mul_f32 v[208:209], v[208:209], s[20:21] op_sel_hi:[1,0]
	v_pk_fma_f32 v[206:207], v[148:149], v[34:35], v[206:207]
	v_pk_fma_f32 v[34:35], v[150:151], v[32:33], v[204:205]
	v_pk_fma_f32 v[38:39], v[148:149], v[38:39], v[210:211]
	v_pk_fma_f32 v[36:37], v[150:151], v[36:37], v[208:209]
	v_cvt_pk_bf16_f32 v32, v36, v37
	v_cvt_pk_bf16_f32 v33, v38, v39
	v_cvt_pk_bf16_f32 v34, v34, v35
	v_cvt_pk_bf16_f32 v35, v206, v207
	global_store_dwordx4 v129, v[32:35], s[14:15] offset:256
	s_waitcnt vmcnt(13)
	v_add_u32_e32 v128, 0x50000, v245
	v_pk_mul_f32 v[214:215], v[214:215], s[20:21] op_sel_hi:[1,0]
	v_pk_mul_f32 v[212:213], v[212:213], s[20:21] op_sel_hi:[1,0]
	v_pk_mul_f32 v[218:219], v[218:219], s[20:21] op_sel_hi:[1,0]
	v_pk_mul_f32 v[216:217], v[216:217], s[20:21] op_sel_hi:[1,0]
	v_pk_fma_f32 v[214:215], v[148:149], v[26:27], v[214:215]
	v_pk_fma_f32 v[26:27], v[150:151], v[24:25], v[212:213]
	v_pk_fma_f32 v[30:31], v[148:149], v[30:31], v[218:219]
	v_pk_fma_f32 v[28:29], v[150:151], v[28:29], v[216:217]
	v_cvt_pk_bf16_f32 v24, v28, v29
	v_cvt_pk_bf16_f32 v25, v30, v31
	v_cvt_pk_bf16_f32 v26, v26, v27
	v_cvt_pk_bf16_f32 v27, v214, v215
	global_store_dwordx4 v128, v[24:27], s[14:15]
	s_waitcnt vmcnt(11)
	v_pk_mul_f32 v[222:223], v[222:223], s[20:21] op_sel_hi:[1,0]
	v_pk_mul_f32 v[220:221], v[220:221], s[20:21] op_sel_hi:[1,0]
	v_pk_mul_f32 v[226:227], v[226:227], s[20:21] op_sel_hi:[1,0]
	v_pk_mul_f32 v[224:225], v[224:225], s[20:21] op_sel_hi:[1,0]
	v_pk_fma_f32 v[222:223], v[148:149], v[18:19], v[222:223]
	v_pk_fma_f32 v[18:19], v[150:151], v[16:17], v[220:221]
	v_pk_fma_f32 v[22:23], v[148:149], v[22:23], v[226:227]
	v_pk_fma_f32 v[20:21], v[150:151], v[20:21], v[224:225]
	v_cvt_pk_bf16_f32 v16, v20, v21
	v_cvt_pk_bf16_f32 v17, v22, v23
	v_cvt_pk_bf16_f32 v18, v18, v19
	v_cvt_pk_bf16_f32 v19, v222, v223
	global_store_dwordx4 v128, v[16:19], s[14:15] offset:256
	s_waitcnt vmcnt(9)
	v_add_u32_e32 v129, 0x58000, v245
	v_pk_mul_f32 v[230:231], v[230:231], s[20:21] op_sel_hi:[1,0]
	v_pk_mul_f32 v[228:229], v[228:229], s[20:21] op_sel_hi:[1,0]
	v_pk_mul_f32 v[234:235], v[234:235], s[20:21] op_sel_hi:[1,0]
	v_pk_mul_f32 v[232:233], v[232:233], s[20:21] op_sel_hi:[1,0]
	v_pk_fma_f32 v[230:231], v[148:149], v[10:11], v[230:231]
	v_pk_fma_f32 v[10:11], v[150:151], v[8:9], v[228:229]
	v_pk_fma_f32 v[14:15], v[148:149], v[14:15], v[234:235]
	v_pk_fma_f32 v[12:13], v[150:151], v[12:13], v[232:233]
	v_cvt_pk_bf16_f32 v8, v12, v13
	v_cvt_pk_bf16_f32 v9, v14, v15
	v_cvt_pk_bf16_f32 v10, v10, v11
	v_cvt_pk_bf16_f32 v11, v230, v231
	global_store_dwordx4 v129, v[8:11], s[14:15]
	s_waitcnt vmcnt(7)
	v_pk_mul_f32 v[238:239], v[238:239], s[20:21] op_sel_hi:[1,0]
	v_pk_mul_f32 v[236:237], v[236:237], s[20:21] op_sel_hi:[1,0]
	v_pk_mul_f32 v[242:243], v[242:243], s[20:21] op_sel_hi:[1,0]
	v_pk_mul_f32 v[240:241], v[240:241], s[20:21] op_sel_hi:[1,0]
	v_pk_fma_f32 v[238:239], v[148:149], v[2:3], v[238:239]
	v_pk_fma_f32 v[2:3], v[150:151], v[0:1], v[236:237]
	v_pk_fma_f32 v[6:7], v[148:149], v[6:7], v[242:243]
	v_pk_fma_f32 v[4:5], v[150:151], v[4:5], v[240:241]
	v_cvt_pk_bf16_f32 v0, v4, v5
	v_cvt_pk_bf16_f32 v1, v6, v7
	v_cvt_pk_bf16_f32 v2, v2, v3
	v_cvt_pk_bf16_f32 v3, v238, v239
	global_store_dwordx4 v129, v[0:3], s[14:15] offset:256
.Lepr_done:
	s_and_b64 vcc, exec, s[2:3]
	s_mov_b64 s[2:3], -1
	s_cbranch_vccnz .LBB0_676
	s_andn2_b64 vcc, exec, s[78:79]
	s_cbranch_vccnz .LBB0_675
	s_barrier
	s_branch .LBB0_675
